# gated-DeltaNet: state update issued right after the solve (table load moved behind it)
# speedup vs baseline: 1.0122x; 1.0122x over previous
; __device__ __forceinline__ void gdn_item(const Params& p, int item, float* sm) {
;     ...
;         const float ks = dpp_sum16(pa + pb2);
;         const float qs = dpp_sum16(qa + qb2);
;         const float coef = be * (v - g * ks);
;         const float oo = g * qs + coef * qk;
;         S[0] = g * S[0] + coef * k0.x; S[1] = g * S[1] + coef * k0.y; S[2] = g * S[2] + coef * k0.z; S[3] = g * S[3] + coef * k0.w;
;         S[4] = g * S[4] + coef * k1.x; S[5] = g * S[5] + coef * k1.y; S[6] = g * S[6] + coef * k1.z; S[7] = g * S[7] + coef * k1.w;
;         oreg[t] = oo * 0.08838834764831845f;
;       }
;       if (sub == 0) {
; #pragma unroll
;         for (int t = 0; t < TC; t++) bo[t * 16 + cw] = oreg[t];
;       }
;     }
;     if (ch + 1 < NCH) GDN_STORE(bi ^ 1)
;     __syncthreads();
;     {
;       const float ov = sm[bi * BUF + 2 * TC * 128 + TC * 16 + 2 * TC + ltt * 16 + lseg];
;       O[(rowb + t0 + ltt) * D + 512 + h * 128 + c0 + lseg] = f2bf(ov);
.Lgd_upd:
	s_nop 2
	v_mfma_f32_16x16x4_f32 v[12:15], v36, v100, v[12:15]
	v_mfma_f32_16x16x4_f32 v[16:19], v40, v100, v[16:19]
	v_mfma_f32_16x16x4_f32 v[12:15], v37, v101, v[12:15]
	v_mfma_f32_16x16x4_f32 v[16:19], v41, v101, v[16:19]
	v_mfma_f32_16x16x4_f32 v[12:15], v38, v102, v[12:15]
	v_mfma_f32_16x16x4_f32 v[16:19], v42, v102, v[16:19]
	v_mfma_f32_16x16x4_f32 v[12:15], v39, v103, v[12:15]
	v_mfma_f32_16x16x4_f32 v[16:19], v43, v103, v[16:19]
	global_load_dwordx4 v[92:95], v59, s[14:15]
	s_cmp_lt_u32 s0, 0x1ff
	s_cselect_b32 s101, 0x400, 0
	s_add_u32 s14, s14, s101
	s_addc_u32 s15, s15, 0
	s_cmp_eq_u32 s12, s100
	s_cbranch_scc0 .Lgd_noout
	s_nop 7
	s_nop 3
	v_mul_f32_e32 v104, v104, v52
	v_mul_f32_e32 v105, v105, v53
	v_mul_f32_e32 v106, v106, v54
	v_mul_f32_e32 v107, v107, v55
	v_cvt_pk_bf16_f32 v104, v104, v104
	v_cvt_pk_bf16_f32 v105, v105, v105
	v_cvt_pk_bf16_f32 v106, v106, v106
	v_cvt_pk_bf16_f32 v107, v107, v107
	global_store_short v57, v104, s[8:9]
	global_store_short v57, v105, s[8:9] offset:2048
	global_store_short v58, v106, s[8:9]
	global_store_short v58, v107, s[8:9] offset:2048
